# rope epilogue: shuffle pipelining restructured so at most 8 LDS ops are outstanding (wait, issue next shuffles, compute)
# baseline (speedup 1.0000x reference)
; __device__ __forceinline__ unsigned cvt_pk_bf16(float lo, float hi) { const f32x2c v = {lo, hi}; const bf16x2c b = __builtin_convertvector(v, bf16x2c); return __builtin_bit_cast(unsigned, b); }
; #define PG8_GAS __attribute__((address_space(1)))
;     __device__ __forceinline__ void operator()(const f32x4 (&acc)[2][2][4][2], const Unit& u, int wr, int wc, int fr, int fq) const {
;     ...
;             const int wcol = (u.pn & 1) * 256 + bj * HALF + wc * 32 + 8 * fq;
;             if (seg < 3) {
;                 const int head = wcol >> 6, ch = wcol & 63;
;                 const bool rotw = (seg < 2) && ((wc & 1) == 0);
; #pragma unroll
;                 for (int ai = 0; ai < 2; ++ai)
; #pragma unroll
;                     for (int m = 0; m < 4; ++m) {
;                         const int r = rbase + ai * HALF + m * 16; const int s = r & 8191;
;                         f32x4 v0 = acc[ai][bj][m][0], v1 = acc[ai][bj][m][1];
;                         if (rotw) {
;                             f32x4 p0, p1;
; #pragma unroll
;                             for (int j = 0; j < 4; ++j) { p0[j] = __shfl_xor(v0[j], 16); p1[j] = __shfl_xor(v1[j], 16); }
;                             if (fq < 2) {
;                                 const f32x4 c0 = *(const PG8_GAS f32x4*)(rope + (size_t)r * 16), c1 = *(const PG8_GAS f32x4*)(rope + (size_t)r * 16 + 4);
;                                 const f32x4 s0 = *(const PG8_GAS f32x4*)(rope + (size_t)r * 16 + 8), s1 = *(const PG8_GAS f32x4*)(rope + (size_t)r * 16 + 12);
;                                 if (fq == 0) { v0 = v0 * c0 - p0 * s0; v1 = v1 * c1 - p1 * s1; }
;                                 else { v0 = v0 * c0 + p0 * s0; v1 = v1 * c1 + p1 * s1; }
;                             }
;                         }
;                         if (seg == 0) { v0 = v0 * 0.18033688011112042f; v1 = v1 * 0.18033688011112042f; }
;                         u32x4 w; w.x = cvt_pk_bf16(v0[0], v0[1]); w.y = cvt_pk_bf16(v0[2], v0[3]); w.z = cvt_pk_bf16(v1[0], v1[1]); w.w = cvt_pk_bf16(v1[2], v1[3]);
;                         *(PG8_GAS u32x4*)(segp + ((size_t)((b * 8 + head) * 8192 + s)) * 64 + ch) = w;
.Lrope_go:
	s_cmp_lt_u32 s0, 2
	s_cselect_b32 s28, s78, 1.0
	s_mov_b32 s29, 0
	s_lshr_b32 s30, s0, 1
	s_lshl_b32 s31, s30, 26
	s_add_u32 s26, s92, s31
	s_addc_u32 s27, s93, 0
	v_readlane_b32 s30, v255, 12
	s_and_b32 s31, s0, 1
	s_lshl_b32 s31, s31, 2
	s_lshr_b32 s32, s30, 6
	s_add_i32 s31, s31, s32
	s_lshr_b32 s32, s54, 5
	s_lshl_b32 s32, s32, 3
	s_add_i32 s31, s31, s32
	s_lshl_b32 s31, s31, 20
	s_and_b32 s32, s54, 31
	s_lshl_b32 s32, s32, 15
	s_add_u32 s31, s31, s32
	s_add_u32 s26, s26, s31
	s_addc_u32 s27, s27, 0
	s_add_u32 s98, s26, 0x200000
	s_addc_u32 s99, s27, 0
	s_and_b32 s32, s30, 32
	s_lshl_b32 s32, s32, 1
	v_lshlrev_b32_e32 v169, 7, v160
	v_lshl_add_u32 v169, v161, 1, v169
	v_add_u32_e32 v169, s32, v169
	v_readlane_b32 s30, v255, 15
	s_nop 3
	s_cmp_lg_u32 s30, 0
	s_cbranch_scc0 .Lrope_plain
	s_lshl_b32 s30, s54, 14
	s_add_u32 s24, s48, s30
	s_addc_u32 s25, s49, 0
	v_lshlrev_b32_e32 v168, 6, v160
	v_lshlrev_b32_e32 v202, 2, v207
	v_cmp_eq_u32_e32 vcc, 0, v161
	v_bfrev_b32_e32 v244, 1
	s_nop 0
	v_cndmask_b32_e32 v252, 0, v244, vcc
	global_load_dwordx4 v[128:131], v168, s[24:25] offset:0
	global_load_dwordx4 v[132:135], v168, s[24:25] offset:16
	global_load_dwordx4 v[136:139], v168, s[24:25] offset:32
	global_load_dwordx4 v[140:143], v168, s[24:25] offset:48
	global_load_dwordx4 v[180:183], v168, s[24:25] offset:1024
	global_load_dwordx4 v[184:187], v168, s[24:25] offset:1040
	global_load_dwordx4 v[188:191], v168, s[24:25] offset:1056
	global_load_dwordx4 v[192:195], v168, s[24:25] offset:1072
	global_load_dwordx4 v[214:217], v168, s[24:25] offset:2048
	global_load_dwordx4 v[218:221], v168, s[24:25] offset:2064
	global_load_dwordx4 v[222:225], v168, s[24:25] offset:2080
	global_load_dwordx4 v[226:229], v168, s[24:25] offset:2096
	ds_bpermute_b32 v230, v202, v120
	ds_bpermute_b32 v231, v202, v121
	ds_bpermute_b32 v232, v202, v122
	ds_bpermute_b32 v233, v202, v123
	ds_bpermute_b32 v234, v202, v124
	ds_bpermute_b32 v235, v202, v125
	ds_bpermute_b32 v236, v202, v126
	ds_bpermute_b32 v237, v202, v127
	s_waitcnt lgkmcnt(0)
	ds_bpermute_b32 v196, v202, v56
	ds_bpermute_b32 v197, v202, v57
	ds_bpermute_b32 v198, v202, v58
	ds_bpermute_b32 v199, v202, v59
	ds_bpermute_b32 v156, v202, v60
	ds_bpermute_b32 v157, v202, v61
	ds_bpermute_b32 v158, v202, v62
	ds_bpermute_b32 v159, v202, v63
	s_waitcnt vmcnt(8)
	v_pk_mul_f32 v[230:231], v[136:137], v[230:231]
	v_pk_mul_f32 v[232:233], v[138:139], v[232:233]
	v_pk_mul_f32 v[244:245], v[120:121], v[128:129]
	v_pk_mul_f32 v[246:247], v[122:123], v[130:131]
	v_xor_b32_e32 v230, v252, v230
	v_xor_b32_e32 v231, v252, v231
	v_xor_b32_e32 v232, v252, v232
	v_xor_b32_e32 v233, v252, v233
	v_pk_add_f32 v[244:245], v[244:245], v[230:231]
	v_pk_add_f32 v[246:247], v[246:247], v[232:233]
	v_cndmask_b32_e64 v120, v120, v244, s[4:5]
	v_cndmask_b32_e64 v121, v121, v245, s[4:5]
	v_cndmask_b32_e64 v122, v122, v246, s[4:5]
	v_cndmask_b32_e64 v123, v123, v247, s[4:5]
	v_pk_mul_f32 v[234:235], v[140:141], v[234:235]
	v_pk_mul_f32 v[236:237], v[142:143], v[236:237]
	v_pk_mul_f32 v[244:245], v[124:125], v[132:133]
	v_pk_mul_f32 v[246:247], v[126:127], v[134:135]
	v_xor_b32_e32 v234, v252, v234
	v_xor_b32_e32 v235, v252, v235
	v_xor_b32_e32 v236, v252, v236
	v_xor_b32_e32 v237, v252, v237
	v_pk_add_f32 v[244:245], v[244:245], v[234:235]
	v_pk_add_f32 v[246:247], v[246:247], v[236:237]
	v_cndmask_b32_e64 v124, v124, v244, s[4:5]
	v_cndmask_b32_e64 v125, v125, v245, s[4:5]
	v_cndmask_b32_e64 v126, v126, v246, s[4:5]
	v_cndmask_b32_e64 v127, v127, v247, s[4:5]
	v_pk_mul_f32 v[120:121], v[120:121], s[28:29] op_sel_hi:[1,0]
	v_pk_mul_f32 v[122:123], v[122:123], s[28:29] op_sel_hi:[1,0]
	v_pk_mul_f32 v[124:125], v[124:125], s[28:29] op_sel_hi:[1,0]
	v_pk_mul_f32 v[126:127], v[126:127], s[28:29] op_sel_hi:[1,0]
	v_cvt_pk_bf16_f32 v248, v120, v121
	v_cvt_pk_bf16_f32 v249, v122, v123
	v_cvt_pk_bf16_f32 v250, v124, v125
	v_cvt_pk_bf16_f32 v251, v126, v127
	global_store_dwordx4 v169, v[248:251], s[26:27]
	s_nop 1
	s_waitcnt lgkmcnt(0)
	ds_bpermute_b32 v230, v202, v112
	ds_bpermute_b32 v231, v202, v113
	ds_bpermute_b32 v232, v202, v114
	ds_bpermute_b32 v233, v202, v115
	ds_bpermute_b32 v234, v202, v116
	ds_bpermute_b32 v235, v202, v117
	ds_bpermute_b32 v236, v202, v118
	ds_bpermute_b32 v237, v202, v119
	v_pk_mul_f32 v[196:197], v[136:137], v[196:197]
	v_pk_mul_f32 v[198:199], v[138:139], v[198:199]
	v_pk_mul_f32 v[244:245], v[56:57], v[128:129]
	v_pk_mul_f32 v[246:247], v[58:59], v[130:131]
	v_xor_b32_e32 v196, v252, v196
	v_xor_b32_e32 v197, v252, v197
	v_xor_b32_e32 v198, v252, v198
	v_xor_b32_e32 v199, v252, v199
	v_pk_add_f32 v[244:245], v[244:245], v[196:197]
	v_pk_add_f32 v[246:247], v[246:247], v[198:199]
	v_cndmask_b32_e64 v56, v56, v244, s[4:5]
	v_cndmask_b32_e64 v57, v57, v245, s[4:5]
	v_cndmask_b32_e64 v58, v58, v246, s[4:5]
	v_cndmask_b32_e64 v59, v59, v247, s[4:5]
	v_pk_mul_f32 v[156:157], v[140:141], v[156:157]
	v_pk_mul_f32 v[158:159], v[142:143], v[158:159]
	v_pk_mul_f32 v[244:245], v[60:61], v[132:133]
	v_pk_mul_f32 v[246:247], v[62:63], v[134:135]
	v_xor_b32_e32 v156, v252, v156
	v_xor_b32_e32 v157, v252, v157
	v_xor_b32_e32 v158, v252, v158
	v_xor_b32_e32 v159, v252, v159
	v_pk_add_f32 v[244:245], v[244:245], v[156:157]
	v_pk_add_f32 v[246:247], v[246:247], v[158:159]
	v_cndmask_b32_e64 v60, v60, v244, s[4:5]
	v_cndmask_b32_e64 v61, v61, v245, s[4:5]
	v_cndmask_b32_e64 v62, v62, v246, s[4:5]
	v_cndmask_b32_e64 v63, v63, v247, s[4:5]
	v_pk_mul_f32 v[56:57], v[56:57], s[28:29] op_sel_hi:[1,0]
	v_pk_mul_f32 v[58:59], v[58:59], s[28:29] op_sel_hi:[1,0]
	v_pk_mul_f32 v[60:61], v[60:61], s[28:29] op_sel_hi:[1,0]
	v_pk_mul_f32 v[62:63], v[62:63], s[28:29] op_sel_hi:[1,0]
	v_cvt_pk_bf16_f32 v248, v56, v57
	v_cvt_pk_bf16_f32 v249, v58, v59
	v_cvt_pk_bf16_f32 v250, v60, v61
	v_cvt_pk_bf16_f32 v251, v62, v63
	global_store_dwordx4 v169, v[248:251], s[98:99]
	s_nop 1
	s_add_u32 s26, s26, 0x800
	s_addc_u32 s27, s27, 0
	s_add_u32 s98, s98, 0x800
	s_addc_u32 s99, s99, 0
	global_load_dwordx4 v[128:131], v168, s[24:25] offset:3072
	global_load_dwordx4 v[132:135], v168, s[24:25] offset:3088
	global_load_dwordx4 v[136:139], v168, s[24:25] offset:3104
	global_load_dwordx4 v[140:143], v168, s[24:25] offset:3120
	s_add_u32 s24, s24, 0x2000
	s_addc_u32 s25, s25, 0
	s_waitcnt lgkmcnt(0)
; __device__ __forceinline__ unsigned cvt_pk_bf16(float lo, float hi) { const f32x2c v = {lo, hi}; const bf16x2c b = __builtin_convertvector(v, bf16x2c); return __builtin_bit_cast(unsigned, b); }
; #define PG8_GAS __attribute__((address_space(1)))
;     __device__ __forceinline__ void operator()(const f32x4 (&acc)[2][2][4][2], const Unit& u, int wr, int wc, int fr, int fq) const {
;     ...
;                         const int r = rbase + ai * HALF + m * 16; const int s = r & 8191;
;                         f32x4 v0 = acc[ai][bj][m][0], v1 = acc[ai][bj][m][1];
;                         if (rotw) {
;                             f32x4 p0, p1;
; #pragma unroll
;                             for (int j = 0; j < 4; ++j) { p0[j] = __shfl_xor(v0[j], 16); p1[j] = __shfl_xor(v1[j], 16); }
;                             if (fq < 2) {
;                                 const f32x4 c0 = *(const PG8_GAS f32x4*)(rope + (size_t)r * 16), c1 = *(const PG8_GAS f32x4*)(rope + (size_t)r * 16 + 4);
;                                 const f32x4 s0 = *(const PG8_GAS f32x4*)(rope + (size_t)r * 16 + 8), s1 = *(const PG8_GAS f32x4*)(rope + (size_t)r * 16 + 12);
;                                 if (fq == 0) { v0 = v0 * c0 - p0 * s0; v1 = v1 * c1 - p1 * s1; }
;                                 else { v0 = v0 * c0 + p0 * s0; v1 = v1 * c1 + p1 * s1; }
;                             }
;                         }
;                         if (seg == 0) { v0 = v0 * 0.18033688011112042f; v1 = v1 * 0.18033688011112042f; }
;                         u32x4 w; w.x = cvt_pk_bf16(v0[0], v0[1]); w.y = cvt_pk_bf16(v0[2], v0[3]); w.z = cvt_pk_bf16(v1[0], v1[1]); w.w = cvt_pk_bf16(v1[2], v1[3]);
;                         *(PG8_GAS u32x4*)(segp + ((size_t)((b * 8 + head) * 8192 + s)) * 64 + ch) = w;
	ds_bpermute_b32 v196, v202, v48
	ds_bpermute_b32 v197, v202, v49
	ds_bpermute_b32 v198, v202, v50
	ds_bpermute_b32 v199, v202, v51
	ds_bpermute_b32 v156, v202, v52
	ds_bpermute_b32 v157, v202, v53
	ds_bpermute_b32 v158, v202, v54
	ds_bpermute_b32 v159, v202, v55
	s_waitcnt vmcnt(10)
	v_pk_mul_f32 v[230:231], v[188:189], v[230:231]
	v_pk_mul_f32 v[232:233], v[190:191], v[232:233]
	v_pk_mul_f32 v[244:245], v[112:113], v[180:181]
	v_pk_mul_f32 v[246:247], v[114:115], v[182:183]
	v_xor_b32_e32 v230, v252, v230
	v_xor_b32_e32 v231, v252, v231
	v_xor_b32_e32 v232, v252, v232
	v_xor_b32_e32 v233, v252, v233
	v_pk_add_f32 v[244:245], v[244:245], v[230:231]
	v_pk_add_f32 v[246:247], v[246:247], v[232:233]
	v_cndmask_b32_e64 v112, v112, v244, s[4:5]
	v_cndmask_b32_e64 v113, v113, v245, s[4:5]
	v_cndmask_b32_e64 v114, v114, v246, s[4:5]
	v_cndmask_b32_e64 v115, v115, v247, s[4:5]
	v_pk_mul_f32 v[234:235], v[192:193], v[234:235]
	v_pk_mul_f32 v[236:237], v[194:195], v[236:237]
	v_pk_mul_f32 v[244:245], v[116:117], v[184:185]
	v_pk_mul_f32 v[246:247], v[118:119], v[186:187]
	v_xor_b32_e32 v234, v252, v234
	v_xor_b32_e32 v235, v252, v235
	v_xor_b32_e32 v236, v252, v236
	v_xor_b32_e32 v237, v252, v237
	v_pk_add_f32 v[244:245], v[244:245], v[234:235]
	v_pk_add_f32 v[246:247], v[246:247], v[236:237]
	v_cndmask_b32_e64 v116, v116, v244, s[4:5]
	v_cndmask_b32_e64 v117, v117, v245, s[4:5]
	v_cndmask_b32_e64 v118, v118, v246, s[4:5]
	v_cndmask_b32_e64 v119, v119, v247, s[4:5]
	v_pk_mul_f32 v[112:113], v[112:113], s[28:29] op_sel_hi:[1,0]
	v_pk_mul_f32 v[114:115], v[114:115], s[28:29] op_sel_hi:[1,0]
	v_pk_mul_f32 v[116:117], v[116:117], s[28:29] op_sel_hi:[1,0]
	v_pk_mul_f32 v[118:119], v[118:119], s[28:29] op_sel_hi:[1,0]
	v_cvt_pk_bf16_f32 v248, v112, v113
	v_cvt_pk_bf16_f32 v249, v114, v115
	v_cvt_pk_bf16_f32 v250, v116, v117
	v_cvt_pk_bf16_f32 v251, v118, v119
	global_store_dwordx4 v169, v[248:251], s[26:27]
	s_nop 1
	s_waitcnt lgkmcnt(0)
	ds_bpermute_b32 v230, v202, v104
	ds_bpermute_b32 v231, v202, v105
	ds_bpermute_b32 v232, v202, v106
	ds_bpermute_b32 v233, v202, v107
	ds_bpermute_b32 v234, v202, v108
	ds_bpermute_b32 v235, v202, v109
	ds_bpermute_b32 v236, v202, v110
	ds_bpermute_b32 v237, v202, v111
	v_pk_mul_f32 v[196:197], v[188:189], v[196:197]
	v_pk_mul_f32 v[198:199], v[190:191], v[198:199]
	v_pk_mul_f32 v[244:245], v[48:49], v[180:181]
	v_pk_mul_f32 v[246:247], v[50:51], v[182:183]
	v_xor_b32_e32 v196, v252, v196
	v_xor_b32_e32 v197, v252, v197
	v_xor_b32_e32 v198, v252, v198
	v_xor_b32_e32 v199, v252, v199
	v_pk_add_f32 v[244:245], v[244:245], v[196:197]
	v_pk_add_f32 v[246:247], v[246:247], v[198:199]
	v_cndmask_b32_e64 v48, v48, v244, s[4:5]
	v_cndmask_b32_e64 v49, v49, v245, s[4:5]
	v_cndmask_b32_e64 v50, v50, v246, s[4:5]
	v_cndmask_b32_e64 v51, v51, v247, s[4:5]
	v_pk_mul_f32 v[156:157], v[192:193], v[156:157]
	v_pk_mul_f32 v[158:159], v[194:195], v[158:159]
	v_pk_mul_f32 v[244:245], v[52:53], v[184:185]
	v_pk_mul_f32 v[246:247], v[54:55], v[186:187]
	v_xor_b32_e32 v156, v252, v156
	v_xor_b32_e32 v157, v252, v157
	v_xor_b32_e32 v158, v252, v158
	v_xor_b32_e32 v159, v252, v159
	v_pk_add_f32 v[244:245], v[244:245], v[156:157]
	v_pk_add_f32 v[246:247], v[246:247], v[158:159]
	v_cndmask_b32_e64 v52, v52, v244, s[4:5]
	v_cndmask_b32_e64 v53, v53, v245, s[4:5]
	v_cndmask_b32_e64 v54, v54, v246, s[4:5]
	v_cndmask_b32_e64 v55, v55, v247, s[4:5]
	v_pk_mul_f32 v[48:49], v[48:49], s[28:29] op_sel_hi:[1,0]
	v_pk_mul_f32 v[50:51], v[50:51], s[28:29] op_sel_hi:[1,0]
	v_pk_mul_f32 v[52:53], v[52:53], s[28:29] op_sel_hi:[1,0]
	v_pk_mul_f32 v[54:55], v[54:55], s[28:29] op_sel_hi:[1,0]
	v_cvt_pk_bf16_f32 v248, v48, v49
	v_cvt_pk_bf16_f32 v249, v50, v51
	v_cvt_pk_bf16_f32 v250, v52, v53
	v_cvt_pk_bf16_f32 v251, v54, v55
	global_store_dwordx4 v169, v[248:251], s[98:99]
	s_nop 1
	s_add_u32 s26, s26, 0x800
	s_addc_u32 s27, s27, 0
	s_add_u32 s98, s98, 0x800
	s_addc_u32 s99, s99, 0
	global_load_dwordx4 v[180:183], v168, s[24:25] offset:0
	global_load_dwordx4 v[184:187], v168, s[24:25] offset:16
	global_load_dwordx4 v[188:191], v168, s[24:25] offset:32
	global_load_dwordx4 v[192:195], v168, s[24:25] offset:48
	s_waitcnt lgkmcnt(0)
	ds_bpermute_b32 v196, v202, v40
	ds_bpermute_b32 v197, v202, v41
	ds_bpermute_b32 v198, v202, v42
	ds_bpermute_b32 v199, v202, v43
	ds_bpermute_b32 v156, v202, v44
	ds_bpermute_b32 v157, v202, v45
	ds_bpermute_b32 v158, v202, v46
	ds_bpermute_b32 v159, v202, v47
	s_waitcnt vmcnt(12)
	v_pk_mul_f32 v[230:231], v[222:223], v[230:231]
	v_pk_mul_f32 v[232:233], v[224:225], v[232:233]
	v_pk_mul_f32 v[244:245], v[104:105], v[214:215]
	v_pk_mul_f32 v[246:247], v[106:107], v[216:217]
	v_xor_b32_e32 v230, v252, v230
	v_xor_b32_e32 v231, v252, v231
	v_xor_b32_e32 v232, v252, v232
	v_xor_b32_e32 v233, v252, v233
	v_pk_add_f32 v[244:245], v[244:245], v[230:231]
	v_pk_add_f32 v[246:247], v[246:247], v[232:233]
	v_cndmask_b32_e64 v104, v104, v244, s[4:5]
	v_cndmask_b32_e64 v105, v105, v245, s[4:5]
	v_cndmask_b32_e64 v106, v106, v246, s[4:5]
	v_cndmask_b32_e64 v107, v107, v247, s[4:5]
	v_pk_mul_f32 v[234:235], v[226:227], v[234:235]
	v_pk_mul_f32 v[236:237], v[228:229], v[236:237]
	v_pk_mul_f32 v[244:245], v[108:109], v[218:219]
	v_pk_mul_f32 v[246:247], v[110:111], v[220:221]
	v_xor_b32_e32 v234, v252, v234
	v_xor_b32_e32 v235, v252, v235
	v_xor_b32_e32 v236, v252, v236
	v_xor_b32_e32 v237, v252, v237
	v_pk_add_f32 v[244:245], v[244:245], v[234:235]
	v_pk_add_f32 v[246:247], v[246:247], v[236:237]
	v_cndmask_b32_e64 v108, v108, v244, s[4:5]
	v_cndmask_b32_e64 v109, v109, v245, s[4:5]
	v_cndmask_b32_e64 v110, v110, v246, s[4:5]
	v_cndmask_b32_e64 v111, v111, v247, s[4:5]
	v_pk_mul_f32 v[104:105], v[104:105], s[28:29] op_sel_hi:[1,0]
	v_pk_mul_f32 v[106:107], v[106:107], s[28:29] op_sel_hi:[1,0]
	v_pk_mul_f32 v[108:109], v[108:109], s[28:29] op_sel_hi:[1,0]
	v_pk_mul_f32 v[110:111], v[110:111], s[28:29] op_sel_hi:[1,0]
	v_cvt_pk_bf16_f32 v248, v104, v105
	v_cvt_pk_bf16_f32 v249, v106, v107
	v_cvt_pk_bf16_f32 v250, v108, v109
	v_cvt_pk_bf16_f32 v251, v110, v111
	global_store_dwordx4 v169, v[248:251], s[26:27]
	s_nop 1
	s_waitcnt lgkmcnt(0)
; __device__ __forceinline__ unsigned cvt_pk_bf16(float lo, float hi) { const f32x2c v = {lo, hi}; const bf16x2c b = __builtin_convertvector(v, bf16x2c); return __builtin_bit_cast(unsigned, b); }
; #define PG8_GAS __attribute__((address_space(1)))
;     __device__ __forceinline__ void operator()(const f32x4 (&acc)[2][2][4][2], const Unit& u, int wr, int wc, int fr, int fq) const {
;     ...
;                         const int r = rbase + ai * HALF + m * 16; const int s = r & 8191;
;                         f32x4 v0 = acc[ai][bj][m][0], v1 = acc[ai][bj][m][1];
;                         if (rotw) {
;                             f32x4 p0, p1;
; #pragma unroll
;                             for (int j = 0; j < 4; ++j) { p0[j] = __shfl_xor(v0[j], 16); p1[j] = __shfl_xor(v1[j], 16); }
;                             if (fq < 2) {
;                                 const f32x4 c0 = *(const PG8_GAS f32x4*)(rope + (size_t)r * 16), c1 = *(const PG8_GAS f32x4*)(rope + (size_t)r * 16 + 4);
;                                 const f32x4 s0 = *(const PG8_GAS f32x4*)(rope + (size_t)r * 16 + 8), s1 = *(const PG8_GAS f32x4*)(rope + (size_t)r * 16 + 12);
;                                 if (fq == 0) { v0 = v0 * c0 - p0 * s0; v1 = v1 * c1 - p1 * s1; }
;                                 else { v0 = v0 * c0 + p0 * s0; v1 = v1 * c1 + p1 * s1; }
;                             }
;                         }
;                         if (seg == 0) { v0 = v0 * 0.18033688011112042f; v1 = v1 * 0.18033688011112042f; }
;                         u32x4 w; w.x = cvt_pk_bf16(v0[0], v0[1]); w.y = cvt_pk_bf16(v0[2], v0[3]); w.z = cvt_pk_bf16(v1[0], v1[1]); w.w = cvt_pk_bf16(v1[2], v1[3]);
;                         *(PG8_GAS u32x4*)(segp + ((size_t)((b * 8 + head) * 8192 + s)) * 64 + ch) = w;
	ds_bpermute_b32 v230, v202, v96
	ds_bpermute_b32 v231, v202, v97
	ds_bpermute_b32 v232, v202, v98
	ds_bpermute_b32 v233, v202, v99
	ds_bpermute_b32 v234, v202, v100
	ds_bpermute_b32 v235, v202, v101
	ds_bpermute_b32 v236, v202, v102
	ds_bpermute_b32 v237, v202, v103
	v_pk_mul_f32 v[196:197], v[222:223], v[196:197]
	v_pk_mul_f32 v[198:199], v[224:225], v[198:199]
	v_pk_mul_f32 v[244:245], v[40:41], v[214:215]
	v_pk_mul_f32 v[246:247], v[42:43], v[216:217]
	v_xor_b32_e32 v196, v252, v196
	v_xor_b32_e32 v197, v252, v197
	v_xor_b32_e32 v198, v252, v198
	v_xor_b32_e32 v199, v252, v199
	v_pk_add_f32 v[244:245], v[244:245], v[196:197]
	v_pk_add_f32 v[246:247], v[246:247], v[198:199]
	v_cndmask_b32_e64 v40, v40, v244, s[4:5]
	v_cndmask_b32_e64 v41, v41, v245, s[4:5]
	v_cndmask_b32_e64 v42, v42, v246, s[4:5]
	v_cndmask_b32_e64 v43, v43, v247, s[4:5]
	v_pk_mul_f32 v[156:157], v[226:227], v[156:157]
	v_pk_mul_f32 v[158:159], v[228:229], v[158:159]
	v_pk_mul_f32 v[244:245], v[44:45], v[218:219]
	v_pk_mul_f32 v[246:247], v[46:47], v[220:221]
	v_xor_b32_e32 v156, v252, v156
	v_xor_b32_e32 v157, v252, v157
	v_xor_b32_e32 v158, v252, v158
	v_xor_b32_e32 v159, v252, v159
	v_pk_add_f32 v[244:245], v[244:245], v[156:157]
	v_pk_add_f32 v[246:247], v[246:247], v[158:159]
	v_cndmask_b32_e64 v44, v44, v244, s[4:5]
	v_cndmask_b32_e64 v45, v45, v245, s[4:5]
	v_cndmask_b32_e64 v46, v46, v246, s[4:5]
	v_cndmask_b32_e64 v47, v47, v247, s[4:5]
	v_pk_mul_f32 v[40:41], v[40:41], s[28:29] op_sel_hi:[1,0]
	v_pk_mul_f32 v[42:43], v[42:43], s[28:29] op_sel_hi:[1,0]
	v_pk_mul_f32 v[44:45], v[44:45], s[28:29] op_sel_hi:[1,0]
	v_pk_mul_f32 v[46:47], v[46:47], s[28:29] op_sel_hi:[1,0]
	v_cvt_pk_bf16_f32 v248, v40, v41
	v_cvt_pk_bf16_f32 v249, v42, v43
	v_cvt_pk_bf16_f32 v250, v44, v45
	v_cvt_pk_bf16_f32 v251, v46, v47
	global_store_dwordx4 v169, v[248:251], s[98:99]
	s_nop 1
	s_add_u32 s26, s26, 0x800
	s_addc_u32 s27, s27, 0
	s_add_u32 s98, s98, 0x800
	s_addc_u32 s99, s99, 0
	global_load_dwordx4 v[214:217], v168, s[24:25] offset:1024
	global_load_dwordx4 v[218:221], v168, s[24:25] offset:1040
	global_load_dwordx4 v[222:225], v168, s[24:25] offset:1056
	global_load_dwordx4 v[226:229], v168, s[24:25] offset:1072
	s_waitcnt lgkmcnt(0)
	ds_bpermute_b32 v196, v202, v32
	ds_bpermute_b32 v197, v202, v33
	ds_bpermute_b32 v198, v202, v34
	ds_bpermute_b32 v199, v202, v35
	ds_bpermute_b32 v156, v202, v36
	ds_bpermute_b32 v157, v202, v37
	ds_bpermute_b32 v158, v202, v38
	ds_bpermute_b32 v159, v202, v39
	s_waitcnt vmcnt(12)
	v_pk_mul_f32 v[230:231], v[136:137], v[230:231]
	v_pk_mul_f32 v[232:233], v[138:139], v[232:233]
	v_pk_mul_f32 v[244:245], v[96:97], v[128:129]
	v_pk_mul_f32 v[246:247], v[98:99], v[130:131]
	v_xor_b32_e32 v230, v252, v230
	v_xor_b32_e32 v231, v252, v231
	v_xor_b32_e32 v232, v252, v232
	v_xor_b32_e32 v233, v252, v233
	v_pk_add_f32 v[244:245], v[244:245], v[230:231]
	v_pk_add_f32 v[246:247], v[246:247], v[232:233]
	v_cndmask_b32_e64 v96, v96, v244, s[4:5]
	v_cndmask_b32_e64 v97, v97, v245, s[4:5]
	v_cndmask_b32_e64 v98, v98, v246, s[4:5]
	v_cndmask_b32_e64 v99, v99, v247, s[4:5]
	v_pk_mul_f32 v[234:235], v[140:141], v[234:235]
	v_pk_mul_f32 v[236:237], v[142:143], v[236:237]
	v_pk_mul_f32 v[244:245], v[100:101], v[132:133]
	v_pk_mul_f32 v[246:247], v[102:103], v[134:135]
	v_xor_b32_e32 v234, v252, v234
	v_xor_b32_e32 v235, v252, v235
	v_xor_b32_e32 v236, v252, v236
	v_xor_b32_e32 v237, v252, v237
	v_pk_add_f32 v[244:245], v[244:245], v[234:235]
	v_pk_add_f32 v[246:247], v[246:247], v[236:237]
	v_cndmask_b32_e64 v100, v100, v244, s[4:5]
	v_cndmask_b32_e64 v101, v101, v245, s[4:5]
	v_cndmask_b32_e64 v102, v102, v246, s[4:5]
	v_cndmask_b32_e64 v103, v103, v247, s[4:5]
	v_pk_mul_f32 v[96:97], v[96:97], s[28:29] op_sel_hi:[1,0]
	v_pk_mul_f32 v[98:99], v[98:99], s[28:29] op_sel_hi:[1,0]
	v_pk_mul_f32 v[100:101], v[100:101], s[28:29] op_sel_hi:[1,0]
	v_pk_mul_f32 v[102:103], v[102:103], s[28:29] op_sel_hi:[1,0]
	v_cvt_pk_bf16_f32 v248, v96, v97
	v_cvt_pk_bf16_f32 v249, v98, v99
	v_cvt_pk_bf16_f32 v250, v100, v101
	v_cvt_pk_bf16_f32 v251, v102, v103
	global_store_dwordx4 v169, v[248:251], s[26:27]
	s_nop 1
	s_waitcnt lgkmcnt(0)
	ds_bpermute_b32 v230, v202, v88
	ds_bpermute_b32 v231, v202, v89
	ds_bpermute_b32 v232, v202, v90
	ds_bpermute_b32 v233, v202, v91
	ds_bpermute_b32 v234, v202, v92
	ds_bpermute_b32 v235, v202, v93
	ds_bpermute_b32 v236, v202, v94
	ds_bpermute_b32 v237, v202, v95
	v_pk_mul_f32 v[196:197], v[136:137], v[196:197]
	v_pk_mul_f32 v[198:199], v[138:139], v[198:199]
	v_pk_mul_f32 v[244:245], v[32:33], v[128:129]
	v_pk_mul_f32 v[246:247], v[34:35], v[130:131]
	v_xor_b32_e32 v196, v252, v196
	v_xor_b32_e32 v197, v252, v197
	v_xor_b32_e32 v198, v252, v198
	v_xor_b32_e32 v199, v252, v199
	v_pk_add_f32 v[244:245], v[244:245], v[196:197]
	v_pk_add_f32 v[246:247], v[246:247], v[198:199]
	v_cndmask_b32_e64 v32, v32, v244, s[4:5]
	v_cndmask_b32_e64 v33, v33, v245, s[4:5]
	v_cndmask_b32_e64 v34, v34, v246, s[4:5]
	v_cndmask_b32_e64 v35, v35, v247, s[4:5]
	v_pk_mul_f32 v[156:157], v[140:141], v[156:157]
	v_pk_mul_f32 v[158:159], v[142:143], v[158:159]
	v_pk_mul_f32 v[244:245], v[36:37], v[132:133]
	v_pk_mul_f32 v[246:247], v[38:39], v[134:135]
	v_xor_b32_e32 v156, v252, v156
	v_xor_b32_e32 v157, v252, v157
	v_xor_b32_e32 v158, v252, v158
	v_xor_b32_e32 v159, v252, v159
	v_pk_add_f32 v[244:245], v[244:245], v[156:157]
	v_pk_add_f32 v[246:247], v[246:247], v[158:159]
	v_cndmask_b32_e64 v36, v36, v244, s[4:5]
	v_cndmask_b32_e64 v37, v37, v245, s[4:5]
	v_cndmask_b32_e64 v38, v38, v246, s[4:5]
	v_cndmask_b32_e64 v39, v39, v247, s[4:5]
	v_pk_mul_f32 v[32:33], v[32:33], s[28:29] op_sel_hi:[1,0]
	v_pk_mul_f32 v[34:35], v[34:35], s[28:29] op_sel_hi:[1,0]
	v_pk_mul_f32 v[36:37], v[36:37], s[28:29] op_sel_hi:[1,0]
	v_pk_mul_f32 v[38:39], v[38:39], s[28:29] op_sel_hi:[1,0]
	v_cvt_pk_bf16_f32 v248, v32, v33
	v_cvt_pk_bf16_f32 v249, v34, v35
	v_cvt_pk_bf16_f32 v250, v36, v37
	v_cvt_pk_bf16_f32 v251, v38, v39
	global_store_dwordx4 v169, v[248:251], s[98:99]
	s_nop 1
	s_add_u32 s26, s26, 0x2800
	s_addc_u32 s27, s27, 0
	s_add_u32 s98, s98, 0x2800
	s_addc_u32 s99, s99, 0
	global_load_dwordx4 v[128:131], v168, s[24:25] offset:2048
	global_load_dwordx4 v[132:135], v168, s[24:25] offset:2064
	global_load_dwordx4 v[136:139], v168, s[24:25] offset:2080
	global_load_dwordx4 v[140:143], v168, s[24:25] offset:2096
	s_waitcnt lgkmcnt(0)
; __device__ __forceinline__ unsigned cvt_pk_bf16(float lo, float hi) { const f32x2c v = {lo, hi}; const bf16x2c b = __builtin_convertvector(v, bf16x2c); return __builtin_bit_cast(unsigned, b); }
; #define PG8_GAS __attribute__((address_space(1)))
;     __device__ __forceinline__ void operator()(const f32x4 (&acc)[2][2][4][2], const Unit& u, int wr, int wc, int fr, int fq) const {
;     ...
;                         const int r = rbase + ai * HALF + m * 16; const int s = r & 8191;
;                         f32x4 v0 = acc[ai][bj][m][0], v1 = acc[ai][bj][m][1];
;                         if (rotw) {
;                             f32x4 p0, p1;
; #pragma unroll
;                             for (int j = 0; j < 4; ++j) { p0[j] = __shfl_xor(v0[j], 16); p1[j] = __shfl_xor(v1[j], 16); }
;                             if (fq < 2) {
;                                 const f32x4 c0 = *(const PG8_GAS f32x4*)(rope + (size_t)r * 16), c1 = *(const PG8_GAS f32x4*)(rope + (size_t)r * 16 + 4);
;                                 const f32x4 s0 = *(const PG8_GAS f32x4*)(rope + (size_t)r * 16 + 8), s1 = *(const PG8_GAS f32x4*)(rope + (size_t)r * 16 + 12);
;                                 if (fq == 0) { v0 = v0 * c0 - p0 * s0; v1 = v1 * c1 - p1 * s1; }
;                                 else { v0 = v0 * c0 + p0 * s0; v1 = v1 * c1 + p1 * s1; }
;                             }
;                         }
;                         if (seg == 0) { v0 = v0 * 0.18033688011112042f; v1 = v1 * 0.18033688011112042f; }
;                         u32x4 w; w.x = cvt_pk_bf16(v0[0], v0[1]); w.y = cvt_pk_bf16(v0[2], v0[3]); w.z = cvt_pk_bf16(v1[0], v1[1]); w.w = cvt_pk_bf16(v1[2], v1[3]);
;                         *(PG8_GAS u32x4*)(segp + ((size_t)((b * 8 + head) * 8192 + s)) * 64 + ch) = w;
	ds_bpermute_b32 v196, v202, v24
	ds_bpermute_b32 v197, v202, v25
	ds_bpermute_b32 v198, v202, v26
	ds_bpermute_b32 v199, v202, v27
	ds_bpermute_b32 v156, v202, v28
	ds_bpermute_b32 v157, v202, v29
	ds_bpermute_b32 v158, v202, v30
	ds_bpermute_b32 v159, v202, v31
	s_waitcnt vmcnt(12)
	v_pk_mul_f32 v[230:231], v[188:189], v[230:231]
	v_pk_mul_f32 v[232:233], v[190:191], v[232:233]
	v_pk_mul_f32 v[244:245], v[88:89], v[180:181]
	v_pk_mul_f32 v[246:247], v[90:91], v[182:183]
	v_xor_b32_e32 v230, v252, v230
	v_xor_b32_e32 v231, v252, v231
	v_xor_b32_e32 v232, v252, v232
	v_xor_b32_e32 v233, v252, v233
	v_pk_add_f32 v[244:245], v[244:245], v[230:231]
	v_pk_add_f32 v[246:247], v[246:247], v[232:233]
	v_cndmask_b32_e64 v88, v88, v244, s[4:5]
	v_cndmask_b32_e64 v89, v89, v245, s[4:5]
	v_cndmask_b32_e64 v90, v90, v246, s[4:5]
	v_cndmask_b32_e64 v91, v91, v247, s[4:5]
	v_pk_mul_f32 v[234:235], v[192:193], v[234:235]
	v_pk_mul_f32 v[236:237], v[194:195], v[236:237]
	v_pk_mul_f32 v[244:245], v[92:93], v[184:185]
	v_pk_mul_f32 v[246:247], v[94:95], v[186:187]
	v_xor_b32_e32 v234, v252, v234
	v_xor_b32_e32 v235, v252, v235
	v_xor_b32_e32 v236, v252, v236
	v_xor_b32_e32 v237, v252, v237
	v_pk_add_f32 v[244:245], v[244:245], v[234:235]
	v_pk_add_f32 v[246:247], v[246:247], v[236:237]
	v_cndmask_b32_e64 v92, v92, v244, s[4:5]
	v_cndmask_b32_e64 v93, v93, v245, s[4:5]
	v_cndmask_b32_e64 v94, v94, v246, s[4:5]
	v_cndmask_b32_e64 v95, v95, v247, s[4:5]
	v_pk_mul_f32 v[88:89], v[88:89], s[28:29] op_sel_hi:[1,0]
	v_pk_mul_f32 v[90:91], v[90:91], s[28:29] op_sel_hi:[1,0]
	v_pk_mul_f32 v[92:93], v[92:93], s[28:29] op_sel_hi:[1,0]
	v_pk_mul_f32 v[94:95], v[94:95], s[28:29] op_sel_hi:[1,0]
	v_cvt_pk_bf16_f32 v248, v88, v89
	v_cvt_pk_bf16_f32 v249, v90, v91
	v_cvt_pk_bf16_f32 v250, v92, v93
	v_cvt_pk_bf16_f32 v251, v94, v95
	global_store_dwordx4 v169, v[248:251], s[26:27]
	s_nop 1
	s_waitcnt lgkmcnt(0)
	ds_bpermute_b32 v230, v202, v80
	ds_bpermute_b32 v231, v202, v81
	ds_bpermute_b32 v232, v202, v82
	ds_bpermute_b32 v233, v202, v83
	ds_bpermute_b32 v234, v202, v84
	ds_bpermute_b32 v235, v202, v85
	ds_bpermute_b32 v236, v202, v86
	ds_bpermute_b32 v237, v202, v87
	v_pk_mul_f32 v[196:197], v[188:189], v[196:197]
	v_pk_mul_f32 v[198:199], v[190:191], v[198:199]
	v_pk_mul_f32 v[244:245], v[24:25], v[180:181]
	v_pk_mul_f32 v[246:247], v[26:27], v[182:183]
	v_xor_b32_e32 v196, v252, v196
	v_xor_b32_e32 v197, v252, v197
	v_xor_b32_e32 v198, v252, v198
	v_xor_b32_e32 v199, v252, v199
	v_pk_add_f32 v[244:245], v[244:245], v[196:197]
	v_pk_add_f32 v[246:247], v[246:247], v[198:199]
	v_cndmask_b32_e64 v24, v24, v244, s[4:5]
	v_cndmask_b32_e64 v25, v25, v245, s[4:5]
	v_cndmask_b32_e64 v26, v26, v246, s[4:5]
	v_cndmask_b32_e64 v27, v27, v247, s[4:5]
	v_pk_mul_f32 v[156:157], v[192:193], v[156:157]
	v_pk_mul_f32 v[158:159], v[194:195], v[158:159]
	v_pk_mul_f32 v[244:245], v[28:29], v[184:185]
	v_pk_mul_f32 v[246:247], v[30:31], v[186:187]
	v_xor_b32_e32 v156, v252, v156
	v_xor_b32_e32 v157, v252, v157
	v_xor_b32_e32 v158, v252, v158
	v_xor_b32_e32 v159, v252, v159
	v_pk_add_f32 v[244:245], v[244:245], v[156:157]
	v_pk_add_f32 v[246:247], v[246:247], v[158:159]
	v_cndmask_b32_e64 v28, v28, v244, s[4:5]
	v_cndmask_b32_e64 v29, v29, v245, s[4:5]
	v_cndmask_b32_e64 v30, v30, v246, s[4:5]
	v_cndmask_b32_e64 v31, v31, v247, s[4:5]
	v_pk_mul_f32 v[24:25], v[24:25], s[28:29] op_sel_hi:[1,0]
	v_pk_mul_f32 v[26:27], v[26:27], s[28:29] op_sel_hi:[1,0]
	v_pk_mul_f32 v[28:29], v[28:29], s[28:29] op_sel_hi:[1,0]
	v_pk_mul_f32 v[30:31], v[30:31], s[28:29] op_sel_hi:[1,0]
	v_cvt_pk_bf16_f32 v248, v24, v25
	v_cvt_pk_bf16_f32 v249, v26, v27
	v_cvt_pk_bf16_f32 v250, v28, v29
	v_cvt_pk_bf16_f32 v251, v30, v31
	global_store_dwordx4 v169, v[248:251], s[98:99]
	s_nop 1
	s_add_u32 s26, s26, 0x800
	s_addc_u32 s27, s27, 0
	s_add_u32 s98, s98, 0x800
	s_addc_u32 s99, s99, 0
	global_load_dwordx4 v[180:183], v168, s[24:25] offset:3072
	global_load_dwordx4 v[184:187], v168, s[24:25] offset:3088
	global_load_dwordx4 v[188:191], v168, s[24:25] offset:3104
	global_load_dwordx4 v[192:195], v168, s[24:25] offset:3120
	s_waitcnt lgkmcnt(0)
	ds_bpermute_b32 v196, v202, v16
	ds_bpermute_b32 v197, v202, v17
	ds_bpermute_b32 v198, v202, v18
	ds_bpermute_b32 v199, v202, v19
	ds_bpermute_b32 v156, v202, v20
	ds_bpermute_b32 v157, v202, v21
	ds_bpermute_b32 v158, v202, v22
	ds_bpermute_b32 v159, v202, v23
	s_waitcnt vmcnt(12)
	v_pk_mul_f32 v[230:231], v[222:223], v[230:231]
	v_pk_mul_f32 v[232:233], v[224:225], v[232:233]
	v_pk_mul_f32 v[244:245], v[80:81], v[214:215]
	v_pk_mul_f32 v[246:247], v[82:83], v[216:217]
	v_xor_b32_e32 v230, v252, v230
	v_xor_b32_e32 v231, v252, v231
	v_xor_b32_e32 v232, v252, v232
	v_xor_b32_e32 v233, v252, v233
	v_pk_add_f32 v[244:245], v[244:245], v[230:231]
	v_pk_add_f32 v[246:247], v[246:247], v[232:233]
	v_cndmask_b32_e64 v80, v80, v244, s[4:5]
	v_cndmask_b32_e64 v81, v81, v245, s[4:5]
	v_cndmask_b32_e64 v82, v82, v246, s[4:5]
	v_cndmask_b32_e64 v83, v83, v247, s[4:5]
	v_pk_mul_f32 v[234:235], v[226:227], v[234:235]
	v_pk_mul_f32 v[236:237], v[228:229], v[236:237]
	v_pk_mul_f32 v[244:245], v[84:85], v[218:219]
	v_pk_mul_f32 v[246:247], v[86:87], v[220:221]
	v_xor_b32_e32 v234, v252, v234
	v_xor_b32_e32 v235, v252, v235
	v_xor_b32_e32 v236, v252, v236
	v_xor_b32_e32 v237, v252, v237
	v_pk_add_f32 v[244:245], v[244:245], v[234:235]
	v_pk_add_f32 v[246:247], v[246:247], v[236:237]
	v_cndmask_b32_e64 v84, v84, v244, s[4:5]
	v_cndmask_b32_e64 v85, v85, v245, s[4:5]
	v_cndmask_b32_e64 v86, v86, v246, s[4:5]
	v_cndmask_b32_e64 v87, v87, v247, s[4:5]
	v_pk_mul_f32 v[80:81], v[80:81], s[28:29] op_sel_hi:[1,0]
	v_pk_mul_f32 v[82:83], v[82:83], s[28:29] op_sel_hi:[1,0]
	v_pk_mul_f32 v[84:85], v[84:85], s[28:29] op_sel_hi:[1,0]
	v_pk_mul_f32 v[86:87], v[86:87], s[28:29] op_sel_hi:[1,0]
	v_cvt_pk_bf16_f32 v248, v80, v81
	v_cvt_pk_bf16_f32 v249, v82, v83
	v_cvt_pk_bf16_f32 v250, v84, v85
	v_cvt_pk_bf16_f32 v251, v86, v87
	global_store_dwordx4 v169, v[248:251], s[26:27]
	s_nop 1
	s_waitcnt lgkmcnt(0)
; __device__ __forceinline__ unsigned cvt_pk_bf16(float lo, float hi) { const f32x2c v = {lo, hi}; const bf16x2c b = __builtin_convertvector(v, bf16x2c); return __builtin_bit_cast(unsigned, b); }
; #define PG8_GAS __attribute__((address_space(1)))
;     __device__ __forceinline__ void operator()(const f32x4 (&acc)[2][2][4][2], const Unit& u, int wr, int wc, int fr, int fq) const {
;     ...
;                         const int r = rbase + ai * HALF + m * 16; const int s = r & 8191;
;                         f32x4 v0 = acc[ai][bj][m][0], v1 = acc[ai][bj][m][1];
;                         if (rotw) {
;                             f32x4 p0, p1;
; #pragma unroll
;                             for (int j = 0; j < 4; ++j) { p0[j] = __shfl_xor(v0[j], 16); p1[j] = __shfl_xor(v1[j], 16); }
;                             if (fq < 2) {
;                                 const f32x4 c0 = *(const PG8_GAS f32x4*)(rope + (size_t)r * 16), c1 = *(const PG8_GAS f32x4*)(rope + (size_t)r * 16 + 4);
;                                 const f32x4 s0 = *(const PG8_GAS f32x4*)(rope + (size_t)r * 16 + 8), s1 = *(const PG8_GAS f32x4*)(rope + (size_t)r * 16 + 12);
;                                 if (fq == 0) { v0 = v0 * c0 - p0 * s0; v1 = v1 * c1 - p1 * s1; }
;                                 else { v0 = v0 * c0 + p0 * s0; v1 = v1 * c1 + p1 * s1; }
;                             }
;                         }
;                         if (seg == 0) { v0 = v0 * 0.18033688011112042f; v1 = v1 * 0.18033688011112042f; }
;                         u32x4 w; w.x = cvt_pk_bf16(v0[0], v0[1]); w.y = cvt_pk_bf16(v0[2], v0[3]); w.z = cvt_pk_bf16(v1[0], v1[1]); w.w = cvt_pk_bf16(v1[2], v1[3]);
;                         *(PG8_GAS u32x4*)(segp + ((size_t)((b * 8 + head) * 8192 + s)) * 64 + ch) = w;
	ds_bpermute_b32 v230, v202, v72
	ds_bpermute_b32 v231, v202, v73
	ds_bpermute_b32 v232, v202, v74
	ds_bpermute_b32 v233, v202, v75
	ds_bpermute_b32 v234, v202, v76
	ds_bpermute_b32 v235, v202, v77
	ds_bpermute_b32 v236, v202, v78
	ds_bpermute_b32 v237, v202, v79
	v_pk_mul_f32 v[196:197], v[222:223], v[196:197]
	v_pk_mul_f32 v[198:199], v[224:225], v[198:199]
	v_pk_mul_f32 v[244:245], v[16:17], v[214:215]
	v_pk_mul_f32 v[246:247], v[18:19], v[216:217]
	v_xor_b32_e32 v196, v252, v196
	v_xor_b32_e32 v197, v252, v197
	v_xor_b32_e32 v198, v252, v198
	v_xor_b32_e32 v199, v252, v199
	v_pk_add_f32 v[244:245], v[244:245], v[196:197]
	v_pk_add_f32 v[246:247], v[246:247], v[198:199]
	v_cndmask_b32_e64 v16, v16, v244, s[4:5]
	v_cndmask_b32_e64 v17, v17, v245, s[4:5]
	v_cndmask_b32_e64 v18, v18, v246, s[4:5]
	v_cndmask_b32_e64 v19, v19, v247, s[4:5]
	v_pk_mul_f32 v[156:157], v[226:227], v[156:157]
	v_pk_mul_f32 v[158:159], v[228:229], v[158:159]
	v_pk_mul_f32 v[244:245], v[20:21], v[218:219]
	v_pk_mul_f32 v[246:247], v[22:23], v[220:221]
	v_xor_b32_e32 v156, v252, v156
	v_xor_b32_e32 v157, v252, v157
	v_xor_b32_e32 v158, v252, v158
	v_xor_b32_e32 v159, v252, v159
	v_pk_add_f32 v[244:245], v[244:245], v[156:157]
	v_pk_add_f32 v[246:247], v[246:247], v[158:159]
	v_cndmask_b32_e64 v20, v20, v244, s[4:5]
	v_cndmask_b32_e64 v21, v21, v245, s[4:5]
	v_cndmask_b32_e64 v22, v22, v246, s[4:5]
	v_cndmask_b32_e64 v23, v23, v247, s[4:5]
	v_pk_mul_f32 v[16:17], v[16:17], s[28:29] op_sel_hi:[1,0]
	v_pk_mul_f32 v[18:19], v[18:19], s[28:29] op_sel_hi:[1,0]
	v_pk_mul_f32 v[20:21], v[20:21], s[28:29] op_sel_hi:[1,0]
	v_pk_mul_f32 v[22:23], v[22:23], s[28:29] op_sel_hi:[1,0]
	v_cvt_pk_bf16_f32 v248, v16, v17
	v_cvt_pk_bf16_f32 v249, v18, v19
	v_cvt_pk_bf16_f32 v250, v20, v21
	v_cvt_pk_bf16_f32 v251, v22, v23
	global_store_dwordx4 v169, v[248:251], s[98:99]
	s_nop 1
	s_add_u32 s26, s26, 0x800
	s_addc_u32 s27, s27, 0
	s_add_u32 s98, s98, 0x800
	s_addc_u32 s99, s99, 0
	s_waitcnt lgkmcnt(0)
	ds_bpermute_b32 v196, v202, v8
	ds_bpermute_b32 v197, v202, v9
	ds_bpermute_b32 v198, v202, v10
	ds_bpermute_b32 v199, v202, v11
	ds_bpermute_b32 v156, v202, v12
	ds_bpermute_b32 v157, v202, v13
	ds_bpermute_b32 v158, v202, v14
	ds_bpermute_b32 v159, v202, v15
	s_waitcnt vmcnt(8)
	v_pk_mul_f32 v[230:231], v[136:137], v[230:231]
	v_pk_mul_f32 v[232:233], v[138:139], v[232:233]
	v_pk_mul_f32 v[244:245], v[72:73], v[128:129]
	v_pk_mul_f32 v[246:247], v[74:75], v[130:131]
	v_xor_b32_e32 v230, v252, v230
	v_xor_b32_e32 v231, v252, v231
	v_xor_b32_e32 v232, v252, v232
	v_xor_b32_e32 v233, v252, v233
	v_pk_add_f32 v[244:245], v[244:245], v[230:231]
	v_pk_add_f32 v[246:247], v[246:247], v[232:233]
	v_cndmask_b32_e64 v72, v72, v244, s[4:5]
	v_cndmask_b32_e64 v73, v73, v245, s[4:5]
	v_cndmask_b32_e64 v74, v74, v246, s[4:5]
	v_cndmask_b32_e64 v75, v75, v247, s[4:5]
	v_pk_mul_f32 v[234:235], v[140:141], v[234:235]
	v_pk_mul_f32 v[236:237], v[142:143], v[236:237]
	v_pk_mul_f32 v[244:245], v[76:77], v[132:133]
	v_pk_mul_f32 v[246:247], v[78:79], v[134:135]
	v_xor_b32_e32 v234, v252, v234
	v_xor_b32_e32 v235, v252, v235
	v_xor_b32_e32 v236, v252, v236
	v_xor_b32_e32 v237, v252, v237
	v_pk_add_f32 v[244:245], v[244:245], v[234:235]
	v_pk_add_f32 v[246:247], v[246:247], v[236:237]
	v_cndmask_b32_e64 v76, v76, v244, s[4:5]
	v_cndmask_b32_e64 v77, v77, v245, s[4:5]
	v_cndmask_b32_e64 v78, v78, v246, s[4:5]
	v_cndmask_b32_e64 v79, v79, v247, s[4:5]
	v_pk_mul_f32 v[72:73], v[72:73], s[28:29] op_sel_hi:[1,0]
	v_pk_mul_f32 v[74:75], v[74:75], s[28:29] op_sel_hi:[1,0]
	v_pk_mul_f32 v[76:77], v[76:77], s[28:29] op_sel_hi:[1,0]
	v_pk_mul_f32 v[78:79], v[78:79], s[28:29] op_sel_hi:[1,0]
	v_cvt_pk_bf16_f32 v248, v72, v73
	v_cvt_pk_bf16_f32 v249, v74, v75
	v_cvt_pk_bf16_f32 v250, v76, v77
	v_cvt_pk_bf16_f32 v251, v78, v79
	global_store_dwordx4 v169, v[248:251], s[26:27]
	s_nop 1
	s_waitcnt lgkmcnt(0)
; __device__ __forceinline__ unsigned cvt_pk_bf16(float lo, float hi) { const f32x2c v = {lo, hi}; const bf16x2c b = __builtin_convertvector(v, bf16x2c); return __builtin_bit_cast(unsigned, b); }
; #define PG8_GAS __attribute__((address_space(1)))
;     __device__ __forceinline__ void operator()(const f32x4 (&acc)[2][2][4][2], const Unit& u, int wr, int wc, int fr, int fq) const {
;     ...
;                         const int r = rbase + ai * HALF + m * 16; const int s = r & 8191;
;                         f32x4 v0 = acc[ai][bj][m][0], v1 = acc[ai][bj][m][1];
;                         if (rotw) {
;                             f32x4 p0, p1;
; #pragma unroll
;                             for (int j = 0; j < 4; ++j) { p0[j] = __shfl_xor(v0[j], 16); p1[j] = __shfl_xor(v1[j], 16); }
;                             if (fq < 2) {
;                                 const f32x4 c0 = *(const PG8_GAS f32x4*)(rope + (size_t)r * 16), c1 = *(const PG8_GAS f32x4*)(rope + (size_t)r * 16 + 4);
;                                 const f32x4 s0 = *(const PG8_GAS f32x4*)(rope + (size_t)r * 16 + 8), s1 = *(const PG8_GAS f32x4*)(rope + (size_t)r * 16 + 12);
;                                 if (fq == 0) { v0 = v0 * c0 - p0 * s0; v1 = v1 * c1 - p1 * s1; }
;                                 else { v0 = v0 * c0 + p0 * s0; v1 = v1 * c1 + p1 * s1; }
;                             }
;                         }
;                         if (seg == 0) { v0 = v0 * 0.18033688011112042f; v1 = v1 * 0.18033688011112042f; }
;                         u32x4 w; w.x = cvt_pk_bf16(v0[0], v0[1]); w.y = cvt_pk_bf16(v0[2], v0[3]); w.z = cvt_pk_bf16(v1[0], v1[1]); w.w = cvt_pk_bf16(v1[2], v1[3]);
;                         *(PG8_GAS u32x4*)(segp + ((size_t)((b * 8 + head) * 8192 + s)) * 64 + ch) = w;
	ds_bpermute_b32 v230, v202, v64
	ds_bpermute_b32 v231, v202, v65
	ds_bpermute_b32 v232, v202, v66
	ds_bpermute_b32 v233, v202, v67
	ds_bpermute_b32 v234, v202, v68
	ds_bpermute_b32 v235, v202, v69
	ds_bpermute_b32 v236, v202, v70
	ds_bpermute_b32 v237, v202, v71
	v_pk_mul_f32 v[196:197], v[136:137], v[196:197]
	v_pk_mul_f32 v[198:199], v[138:139], v[198:199]
	v_pk_mul_f32 v[244:245], v[8:9], v[128:129]
	v_pk_mul_f32 v[246:247], v[10:11], v[130:131]
	v_xor_b32_e32 v196, v252, v196
	v_xor_b32_e32 v197, v252, v197
	v_xor_b32_e32 v198, v252, v198
	v_xor_b32_e32 v199, v252, v199
	v_pk_add_f32 v[244:245], v[244:245], v[196:197]
	v_pk_add_f32 v[246:247], v[246:247], v[198:199]
	v_cndmask_b32_e64 v8, v8, v244, s[4:5]
	v_cndmask_b32_e64 v9, v9, v245, s[4:5]
	v_cndmask_b32_e64 v10, v10, v246, s[4:5]
	v_cndmask_b32_e64 v11, v11, v247, s[4:5]
	v_pk_mul_f32 v[156:157], v[140:141], v[156:157]
	v_pk_mul_f32 v[158:159], v[142:143], v[158:159]
	v_pk_mul_f32 v[244:245], v[12:13], v[132:133]
	v_pk_mul_f32 v[246:247], v[14:15], v[134:135]
	v_xor_b32_e32 v156, v252, v156
	v_xor_b32_e32 v157, v252, v157
	v_xor_b32_e32 v158, v252, v158
	v_xor_b32_e32 v159, v252, v159
	v_pk_add_f32 v[244:245], v[244:245], v[156:157]
	v_pk_add_f32 v[246:247], v[246:247], v[158:159]
	v_cndmask_b32_e64 v12, v12, v244, s[4:5]
	v_cndmask_b32_e64 v13, v13, v245, s[4:5]
	v_cndmask_b32_e64 v14, v14, v246, s[4:5]
	v_cndmask_b32_e64 v15, v15, v247, s[4:5]
	v_pk_mul_f32 v[8:9], v[8:9], s[28:29] op_sel_hi:[1,0]
	v_pk_mul_f32 v[10:11], v[10:11], s[28:29] op_sel_hi:[1,0]
	v_pk_mul_f32 v[12:13], v[12:13], s[28:29] op_sel_hi:[1,0]
	v_pk_mul_f32 v[14:15], v[14:15], s[28:29] op_sel_hi:[1,0]
	v_cvt_pk_bf16_f32 v248, v8, v9
	v_cvt_pk_bf16_f32 v249, v10, v11
	v_cvt_pk_bf16_f32 v250, v12, v13
	v_cvt_pk_bf16_f32 v251, v14, v15
	global_store_dwordx4 v169, v[248:251], s[98:99]
	s_nop 1
	s_add_u32 s26, s26, 0x800
	s_addc_u32 s27, s27, 0
	s_add_u32 s98, s98, 0x800
	s_addc_u32 s99, s99, 0
	s_waitcnt lgkmcnt(0)
	ds_bpermute_b32 v196, v202, v4
	ds_bpermute_b32 v197, v202, v5
	ds_bpermute_b32 v198, v202, v6
	ds_bpermute_b32 v199, v202, v7
	ds_bpermute_b32 v156, v202, v0
	ds_bpermute_b32 v157, v202, v1
	ds_bpermute_b32 v158, v202, v2
	ds_bpermute_b32 v159, v202, v3
	s_waitcnt vmcnt(4)
	v_pk_mul_f32 v[230:231], v[188:189], v[230:231]
	v_pk_mul_f32 v[232:233], v[190:191], v[232:233]
	v_pk_mul_f32 v[244:245], v[64:65], v[180:181]
	v_pk_mul_f32 v[246:247], v[66:67], v[182:183]
	v_xor_b32_e32 v230, v252, v230
	v_xor_b32_e32 v231, v252, v231
	v_xor_b32_e32 v232, v252, v232
	v_xor_b32_e32 v233, v252, v233
	v_pk_add_f32 v[244:245], v[244:245], v[230:231]
	v_pk_add_f32 v[246:247], v[246:247], v[232:233]
	v_cndmask_b32_e64 v64, v64, v244, s[4:5]
	v_cndmask_b32_e64 v65, v65, v245, s[4:5]
	v_cndmask_b32_e64 v66, v66, v246, s[4:5]
	v_cndmask_b32_e64 v67, v67, v247, s[4:5]
	v_pk_mul_f32 v[234:235], v[192:193], v[234:235]
	v_pk_mul_f32 v[236:237], v[194:195], v[236:237]
	v_pk_mul_f32 v[244:245], v[68:69], v[184:185]
	v_pk_mul_f32 v[246:247], v[70:71], v[186:187]
	v_xor_b32_e32 v234, v252, v234
	v_xor_b32_e32 v235, v252, v235
	v_xor_b32_e32 v236, v252, v236
	v_xor_b32_e32 v237, v252, v237
	v_pk_add_f32 v[244:245], v[244:245], v[234:235]
	v_pk_add_f32 v[246:247], v[246:247], v[236:237]
	v_cndmask_b32_e64 v68, v68, v244, s[4:5]
	v_cndmask_b32_e64 v69, v69, v245, s[4:5]
	v_cndmask_b32_e64 v70, v70, v246, s[4:5]
	v_cndmask_b32_e64 v71, v71, v247, s[4:5]
	v_pk_mul_f32 v[64:65], v[64:65], s[28:29] op_sel_hi:[1,0]
	v_pk_mul_f32 v[66:67], v[66:67], s[28:29] op_sel_hi:[1,0]
	v_pk_mul_f32 v[68:69], v[68:69], s[28:29] op_sel_hi:[1,0]
	v_pk_mul_f32 v[70:71], v[70:71], s[28:29] op_sel_hi:[1,0]
	v_cvt_pk_bf16_f32 v248, v64, v65
	v_cvt_pk_bf16_f32 v249, v66, v67
	v_cvt_pk_bf16_f32 v250, v68, v69
	v_cvt_pk_bf16_f32 v251, v70, v71
	global_store_dwordx4 v169, v[248:251], s[26:27]
	s_nop 1
	s_waitcnt lgkmcnt(0)
	v_pk_mul_f32 v[196:197], v[188:189], v[196:197]
	v_pk_mul_f32 v[198:199], v[190:191], v[198:199]
	v_pk_mul_f32 v[244:245], v[4:5], v[180:181]
	v_pk_mul_f32 v[246:247], v[6:7], v[182:183]
	v_xor_b32_e32 v196, v252, v196
	v_xor_b32_e32 v197, v252, v197
	v_xor_b32_e32 v198, v252, v198
	v_xor_b32_e32 v199, v252, v199
	v_pk_add_f32 v[244:245], v[244:245], v[196:197]
	v_pk_add_f32 v[246:247], v[246:247], v[198:199]
	v_cndmask_b32_e64 v4, v4, v244, s[4:5]
	v_cndmask_b32_e64 v5, v5, v245, s[4:5]
	v_cndmask_b32_e64 v6, v6, v246, s[4:5]
	v_cndmask_b32_e64 v7, v7, v247, s[4:5]
	v_pk_mul_f32 v[156:157], v[192:193], v[156:157]
	v_pk_mul_f32 v[158:159], v[194:195], v[158:159]
	v_pk_mul_f32 v[244:245], v[0:1], v[184:185]
	v_pk_mul_f32 v[246:247], v[2:3], v[186:187]
	v_xor_b32_e32 v156, v252, v156
	v_xor_b32_e32 v157, v252, v157
	v_xor_b32_e32 v158, v252, v158
	v_xor_b32_e32 v159, v252, v159
	v_pk_add_f32 v[244:245], v[244:245], v[156:157]
	v_pk_add_f32 v[246:247], v[246:247], v[158:159]
	v_cndmask_b32_e64 v0, v0, v244, s[4:5]
	v_cndmask_b32_e64 v1, v1, v245, s[4:5]
	v_cndmask_b32_e64 v2, v2, v246, s[4:5]
	v_cndmask_b32_e64 v3, v3, v247, s[4:5]
	v_pk_mul_f32 v[4:5], v[4:5], s[28:29] op_sel_hi:[1,0]
	v_pk_mul_f32 v[6:7], v[6:7], s[28:29] op_sel_hi:[1,0]
	v_pk_mul_f32 v[0:1], v[0:1], s[28:29] op_sel_hi:[1,0]
	v_pk_mul_f32 v[2:3], v[2:3], s[28:29] op_sel_hi:[1,0]
	v_cvt_pk_bf16_f32 v248, v4, v5
	v_cvt_pk_bf16_f32 v249, v6, v7
	v_cvt_pk_bf16_f32 v250, v0, v1
	v_cvt_pk_bf16_f32 v251, v2, v3
	global_store_dwordx4 v169, v[248:251], s[98:99]
	s_nop 1
	s_branch .Lrope_done
